# first-iteration relaxed vmcnt waits extended to F1 (S0,S1 vmcnt(16)) and F2 S1 (not on a phase's first tile), on top of G2/F2 version
# baseline (speedup 1.0000x reference)
.LBB0_783:
	s_add_u32 s2, s4, 0xfffc0080
	s_addc_u32 s3, s5, -1
	s_add_i32 s48, 0, 0x10000
	s_cmp_eq_u32 s47, 12
	s_cselect_b32 s27, s17, s3
	s_cselect_b32 s26, s25, s2
	s_cselect_b32 s3, s15, s46
	s_cselect_b32 s2, s41, s42
	s_add_i32 s50, 0, 0x14000
	v_add_u32_e32 v154, s48, v140
	v_add_u32_e32 v170, s50, v140
	ds_read_b128 v[142:145], v154
	ds_read_b128 v[146:149], v154 offset:1024
	ds_read_b128 v[150:153], v154 offset:2048
	ds_read_b128 v[154:157], v154 offset:3072
	ds_read_b128 v[158:161], v170
	ds_read_b128 v[162:165], v170 offset:1024
	ds_read_b128 v[166:169], v170 offset:2048
	ds_read_b128 v[170:173], v170 offset:3072
	v_lshl_add_u64 v[206:207], s[4:5], 0, v[136:137]
	s_add_i32 m0, s23, 0xc000
	ds_read_b128 v[174:177], v141
	ds_read_b128 v[178:181], v141 offset:1024
	ds_read_b128 v[182:185], v141 offset:2048
	ds_read_b128 v[186:189], v141 offset:3072
	ds_read_b128 v[190:193], v141 offset:4096
	ds_read_b128 v[194:197], v141 offset:5120
	ds_read_b128 v[198:201], v141 offset:6144
	ds_read_b128 v[202:205], v141 offset:7168
	global_load_lds_dwordx4 v[206:207], off
	v_lshl_add_u64 v[206:207], s[4:5], 0, v[138:139]
	s_add_i32 m0, s23, 0xe000
	s_nop 0
	global_load_lds_dwordx4 v[206:207], off
	s_cmp_lg_u32 s47, -2
	s_cbranch_scc1 .Lsw_f10a
	s_waitcnt vmcnt(16)
	s_branch .Lsw_f10b

.Lsw_f10b:
	s_waitcnt lgkmcnt(0)
	s_setprio 1
	s_barrier
	v_mfma_f32_16x16x32_bf16 v[122:125], v[142:145], v[174:177], v[122:125]
	v_mfma_f32_16x16x32_bf16 v[114:117], v[150:153], v[174:177], v[114:117]
	v_mfma_f32_16x16x32_bf16 v[106:109], v[142:145], v[182:185], v[106:109]
	v_mfma_f32_16x16x32_bf16 v[98:101], v[150:153], v[182:185], v[98:101]
	v_mfma_f32_16x16x32_bf16 v[90:93], v[142:145], v[190:193], v[90:93]
	v_mfma_f32_16x16x32_bf16 v[82:85], v[150:153], v[190:193], v[82:85]
	v_mfma_f32_16x16x32_bf16 v[74:77], v[142:145], v[198:201], v[74:77]
	v_mfma_f32_16x16x32_bf16 v[66:69], v[150:153], v[198:201], v[66:69]
	v_mfma_f32_16x16x32_bf16 v[122:125], v[146:149], v[178:181], v[122:125]
	v_mfma_f32_16x16x32_bf16 v[114:117], v[154:157], v[178:181], v[114:117]
	v_mfma_f32_16x16x32_bf16 v[106:109], v[146:149], v[186:189], v[106:109]
	v_mfma_f32_16x16x32_bf16 v[98:101], v[154:157], v[186:189], v[98:101]
	v_mfma_f32_16x16x32_bf16 v[90:93], v[146:149], v[194:197], v[90:93]
	v_mfma_f32_16x16x32_bf16 v[82:85], v[154:157], v[194:197], v[82:85]
	v_mfma_f32_16x16x32_bf16 v[74:77], v[146:149], v[202:205], v[74:77]
	v_mfma_f32_16x16x32_bf16 v[66:69], v[154:157], v[202:205], v[66:69]
	v_mfma_f32_16x16x32_bf16 v[126:129], v[158:161], v[174:177], v[126:129]
	v_mfma_f32_16x16x32_bf16 v[118:121], v[166:169], v[174:177], v[118:121]
	v_mfma_f32_16x16x32_bf16 v[110:113], v[158:161], v[182:185], v[110:113]
	v_mfma_f32_16x16x32_bf16 v[102:105], v[166:169], v[182:185], v[102:105]
	v_mfma_f32_16x16x32_bf16 v[94:97], v[158:161], v[190:193], v[94:97]
	v_mfma_f32_16x16x32_bf16 v[86:89], v[166:169], v[190:193], v[86:89]
	v_mfma_f32_16x16x32_bf16 v[78:81], v[158:161], v[198:201], v[78:81]
	v_mfma_f32_16x16x32_bf16 v[70:73], v[166:169], v[198:201], v[70:73]
	v_mfma_f32_16x16x32_bf16 v[126:129], v[162:165], v[178:181], v[126:129]
	v_mfma_f32_16x16x32_bf16 v[118:121], v[170:173], v[178:181], v[118:121]
	v_mfma_f32_16x16x32_bf16 v[110:113], v[162:165], v[186:189], v[110:113]
	v_mfma_f32_16x16x32_bf16 v[102:105], v[170:173], v[186:189], v[102:105]
	v_mfma_f32_16x16x32_bf16 v[94:97], v[162:165], v[194:197], v[94:97]
	v_mfma_f32_16x16x32_bf16 v[86:89], v[170:173], v[194:197], v[86:89]
	v_mfma_f32_16x16x32_bf16 v[78:81], v[162:165], v[202:205], v[78:81]
	v_mfma_f32_16x16x32_bf16 v[70:73], v[170:173], v[202:205], v[70:73]
	s_barrier
	s_setprio 0
	s_add_i32 s48, s48, s28
	v_lshl_add_u64 v[206:207], s[2:3], 0, v[132:133]
	s_mov_b32 m0, s48
	ds_read_b128 v[174:177], v141 offset:16384
	ds_read_b128 v[178:181], v141 offset:17408
	ds_read_b128 v[182:185], v141 offset:18432
	ds_read_b128 v[186:189], v141 offset:19456
	ds_read_b128 v[190:193], v141 offset:20480
	ds_read_b128 v[194:197], v141 offset:21504
	ds_read_b128 v[198:201], v141 offset:22528
	ds_read_b128 v[202:205], v141 offset:23552
	global_load_lds_dwordx4 v[206:207], off
	s_add_i32 m0, s48, 0x2000
	s_add_u32 s48, s2, 0x40000
	v_lshl_add_u64 v[218:219], s[2:3], 0, v[130:131]
	s_addc_u32 s49, s3, 0
	s_add_i32 s50, s50, s28
	global_load_lds_dwordx4 v[218:219], off
	v_lshl_add_u64 v[222:223], s[48:49], 0, v[132:133]
	s_mov_b32 m0, s50
	v_lshl_add_u64 v[224:225], s[26:27], 0, v[130:131]
	global_load_lds_dwordx4 v[222:223], off
	v_lshl_add_u64 v[222:223], s[48:49], 0, v[130:131]
	s_add_i32 m0, s50, 0x2000
	s_nop 0
	global_load_lds_dwordx4 v[222:223], off
	v_lshl_add_u64 v[222:223], s[26:27], 0, v[132:133]
	s_mov_b32 m0, s23
	s_nop 0
	global_load_lds_dwordx4 v[222:223], off
	s_mov_b32 m0, s31
	s_nop 0
	global_load_lds_dwordx4 v[224:225], off
	s_cmp_lg_u32 s47, -2
	s_cbranch_scc1 .Lsw_f11a
	s_cmp_eq_u32 s37, 1
	s_cbranch_scc1 .Lsw_f11a
	s_waitcnt vmcnt(16)
	s_branch .Lsw_f11b

.Lsw_f11b:
	s_waitcnt lgkmcnt(0)
	s_setprio 1
	s_barrier
	v_mfma_f32_16x16x32_bf16 v[58:61], v[142:145], v[174:177], v[58:61]
	v_mfma_f32_16x16x32_bf16 v[50:53], v[150:153], v[174:177], v[50:53]
	v_mfma_f32_16x16x32_bf16 v[42:45], v[142:145], v[182:185], v[42:45]
	v_mfma_f32_16x16x32_bf16 v[34:37], v[150:153], v[182:185], v[34:37]
	v_mfma_f32_16x16x32_bf16 v[26:29], v[142:145], v[190:193], v[26:29]
	v_mfma_f32_16x16x32_bf16 v[18:21], v[150:153], v[190:193], v[18:21]
	v_mfma_f32_16x16x32_bf16 v[10:13], v[142:145], v[198:201], v[10:13]
	v_mfma_f32_16x16x32_bf16 v[2:5], v[150:153], v[198:201], v[2:5]
	v_mfma_f32_16x16x32_bf16 v[58:61], v[146:149], v[178:181], v[58:61]
	v_mfma_f32_16x16x32_bf16 v[50:53], v[154:157], v[178:181], v[50:53]
	v_mfma_f32_16x16x32_bf16 v[42:45], v[146:149], v[186:189], v[42:45]
	v_mfma_f32_16x16x32_bf16 v[34:37], v[154:157], v[186:189], v[34:37]
	v_mfma_f32_16x16x32_bf16 v[26:29], v[146:149], v[194:197], v[26:29]
	v_mfma_f32_16x16x32_bf16 v[18:21], v[154:157], v[194:197], v[18:21]
	v_mfma_f32_16x16x32_bf16 v[10:13], v[146:149], v[202:205], v[10:13]
	v_mfma_f32_16x16x32_bf16 v[2:5], v[154:157], v[202:205], v[2:5]
	v_mfma_f32_16x16x32_bf16 v[62:65], v[158:161], v[174:177], v[62:65]
	v_mfma_f32_16x16x32_bf16 v[54:57], v[166:169], v[174:177], v[54:57]
	v_mfma_f32_16x16x32_bf16 v[46:49], v[158:161], v[182:185], v[46:49]
	v_mfma_f32_16x16x32_bf16 v[38:41], v[166:169], v[182:185], v[38:41]
	v_mfma_f32_16x16x32_bf16 v[30:33], v[158:161], v[190:193], v[30:33]
	v_mfma_f32_16x16x32_bf16 v[22:25], v[166:169], v[190:193], v[22:25]
	v_mfma_f32_16x16x32_bf16 v[14:17], v[158:161], v[198:201], v[14:17]
	v_mfma_f32_16x16x32_bf16 v[6:9], v[166:169], v[198:201], v[6:9]
	v_mfma_f32_16x16x32_bf16 v[62:65], v[162:165], v[178:181], v[62:65]
	v_mfma_f32_16x16x32_bf16 v[54:57], v[170:173], v[178:181], v[54:57]
	v_mfma_f32_16x16x32_bf16 v[46:49], v[162:165], v[186:189], v[46:49]
	v_mfma_f32_16x16x32_bf16 v[38:41], v[170:173], v[186:189], v[38:41]
	v_mfma_f32_16x16x32_bf16 v[30:33], v[162:165], v[194:197], v[30:33]
	v_mfma_f32_16x16x32_bf16 v[22:25], v[170:173], v[194:197], v[22:25]
	v_mfma_f32_16x16x32_bf16 v[14:17], v[162:165], v[202:205], v[14:17]
	v_mfma_f32_16x16x32_bf16 v[6:9], v[170:173], v[202:205], v[6:9]
	s_barrier
	s_setprio 0
	s_add_i32 s48, 0, 0x18000
	s_add_i32 s49, 0, 0x1c000
	v_add_u32_e32 v154, s48, v140
	v_add_u32_e32 v170, s49, v140
	ds_read_b128 v[142:145], v154
	ds_read_b128 v[146:149], v154 offset:1024
	ds_read_b128 v[150:153], v154 offset:2048
	ds_read_b128 v[154:157], v154 offset:3072
	ds_read_b128 v[158:161], v170
	ds_read_b128 v[162:165], v170 offset:1024
	ds_read_b128 v[166:169], v170 offset:2048
	ds_read_b128 v[170:173], v170 offset:3072
	s_add_u32 s26, s26, 0x40000
	s_addc_u32 s27, s27, 0
	s_mov_b32 m0, s33
	v_lshl_add_u64 v[226:227], s[26:27], 0, v[132:133]
	ds_read_b128 v[174:177], v141 offset:32768
	ds_read_b128 v[178:181], v141 offset:33792
	ds_read_b128 v[182:185], v141 offset:34816
	ds_read_b128 v[186:189], v141 offset:35840
	ds_read_b128 v[190:193], v141 offset:36864
	ds_read_b128 v[194:197], v141 offset:37888
	ds_read_b128 v[198:201], v141 offset:38912
	ds_read_b128 v[202:205], v141 offset:39936
	global_load_lds_dwordx4 v[226:227], off
	v_lshl_add_u64 v[226:227], s[26:27], 0, v[130:131]
	s_mov_b32 m0, s34
	s_nop 0
	global_load_lds_dwordx4 v[226:227], off
	s_waitcnt vmcnt(8)
	s_waitcnt lgkmcnt(0)
	s_setprio 1
	s_barrier
	v_mfma_f32_16x16x32_bf16 v[122:125], v[142:145], v[174:177], v[122:125]
	v_mfma_f32_16x16x32_bf16 v[114:117], v[150:153], v[174:177], v[114:117]
	v_mfma_f32_16x16x32_bf16 v[106:109], v[142:145], v[182:185], v[106:109]
	v_mfma_f32_16x16x32_bf16 v[98:101], v[150:153], v[182:185], v[98:101]
	v_mfma_f32_16x16x32_bf16 v[90:93], v[142:145], v[190:193], v[90:93]
	v_mfma_f32_16x16x32_bf16 v[82:85], v[150:153], v[190:193], v[82:85]
	v_mfma_f32_16x16x32_bf16 v[74:77], v[142:145], v[198:201], v[74:77]
	v_mfma_f32_16x16x32_bf16 v[66:69], v[150:153], v[198:201], v[66:69]
	v_mfma_f32_16x16x32_bf16 v[122:125], v[146:149], v[178:181], v[122:125]
	v_mfma_f32_16x16x32_bf16 v[114:117], v[154:157], v[178:181], v[114:117]
	v_mfma_f32_16x16x32_bf16 v[106:109], v[146:149], v[186:189], v[106:109]
	v_mfma_f32_16x16x32_bf16 v[98:101], v[154:157], v[186:189], v[98:101]
	v_mfma_f32_16x16x32_bf16 v[90:93], v[146:149], v[194:197], v[90:93]
	v_mfma_f32_16x16x32_bf16 v[82:85], v[154:157], v[194:197], v[82:85]
	v_mfma_f32_16x16x32_bf16 v[74:77], v[146:149], v[202:205], v[74:77]
	v_mfma_f32_16x16x32_bf16 v[66:69], v[154:157], v[202:205], v[66:69]
	v_mfma_f32_16x16x32_bf16 v[126:129], v[158:161], v[174:177], v[126:129]
	v_mfma_f32_16x16x32_bf16 v[118:121], v[166:169], v[174:177], v[118:121]
	v_mfma_f32_16x16x32_bf16 v[110:113], v[158:161], v[182:185], v[110:113]
	v_mfma_f32_16x16x32_bf16 v[102:105], v[166:169], v[182:185], v[102:105]
	v_mfma_f32_16x16x32_bf16 v[94:97], v[158:161], v[190:193], v[94:97]
	v_mfma_f32_16x16x32_bf16 v[86:89], v[166:169], v[190:193], v[86:89]
	v_mfma_f32_16x16x32_bf16 v[78:81], v[158:161], v[198:201], v[78:81]
	v_mfma_f32_16x16x32_bf16 v[70:73], v[166:169], v[198:201], v[70:73]
	v_mfma_f32_16x16x32_bf16 v[126:129], v[162:165], v[178:181], v[126:129]
	v_mfma_f32_16x16x32_bf16 v[118:121], v[170:173], v[178:181], v[118:121]
	v_mfma_f32_16x16x32_bf16 v[110:113], v[162:165], v[186:189], v[110:113]
	v_mfma_f32_16x16x32_bf16 v[102:105], v[170:173], v[186:189], v[102:105]
	v_mfma_f32_16x16x32_bf16 v[94:97], v[162:165], v[194:197], v[94:97]
	v_mfma_f32_16x16x32_bf16 v[86:89], v[170:173], v[194:197], v[86:89]
	v_mfma_f32_16x16x32_bf16 v[78:81], v[162:165], v[202:205], v[78:81]
	v_mfma_f32_16x16x32_bf16 v[70:73], v[170:173], v[202:205], v[70:73]
	s_barrier
	s_setprio 0
	s_add_i32 s26, s48, s28
	v_lshl_add_u64 v[206:207], v[206:207], 0, s[44:45]
	s_mov_b32 m0, s26
	ds_read_b128 v[174:177], v141 offset:49152
	ds_read_b128 v[178:181], v141 offset:50176
	ds_read_b128 v[182:185], v141 offset:51200
	ds_read_b128 v[186:189], v141 offset:52224
	ds_read_b128 v[190:193], v141 offset:53248
	ds_read_b128 v[194:197], v141 offset:54272
	ds_read_b128 v[198:201], v141 offset:55296
	ds_read_b128 v[202:205], v141 offset:56320
	global_load_lds_dwordx4 v[206:207], off
	s_add_i32 m0, s26, 0x2000
	s_add_u32 s2, s2, 0x40080
	v_lshl_add_u64 v[206:207], v[218:219], 0, s[44:45]
	s_addc_u32 s3, s3, 0
	s_add_i32 s26, s49, s28
	global_load_lds_dwordx4 v[206:207], off
	v_lshl_add_u64 v[206:207], s[2:3], 0, v[132:133]
	s_mov_b32 m0, s26
	s_nop 0
	global_load_lds_dwordx4 v[206:207], off
	v_lshl_add_u64 v[206:207], s[2:3], 0, v[130:131]
	s_add_i32 m0, s26, 0x2000
	s_nop 0
	global_load_lds_dwordx4 v[206:207], off
	v_lshl_add_u64 v[206:207], v[222:223], 0, s[44:45]
	s_mov_b32 m0, s35
	s_nop 0
	global_load_lds_dwordx4 v[206:207], off
	v_lshl_add_u64 v[206:207], v[224:225], 0, s[44:45]
	s_mov_b32 m0, s36
	s_nop 0
	global_load_lds_dwordx4 v[206:207], off
	s_waitcnt vmcnt(8)
	s_waitcnt lgkmcnt(0)
	s_setprio 1
	s_barrier
	v_mfma_f32_16x16x32_bf16 v[58:61], v[142:145], v[174:177], v[58:61]
	v_mfma_f32_16x16x32_bf16 v[50:53], v[150:153], v[174:177], v[50:53]
	v_mfma_f32_16x16x32_bf16 v[42:45], v[142:145], v[182:185], v[42:45]
	v_mfma_f32_16x16x32_bf16 v[34:37], v[150:153], v[182:185], v[34:37]
	v_mfma_f32_16x16x32_bf16 v[26:29], v[142:145], v[190:193], v[26:29]
	v_mfma_f32_16x16x32_bf16 v[18:21], v[150:153], v[190:193], v[18:21]
	v_mfma_f32_16x16x32_bf16 v[10:13], v[142:145], v[198:201], v[10:13]
	v_mfma_f32_16x16x32_bf16 v[2:5], v[150:153], v[198:201], v[2:5]
	v_mfma_f32_16x16x32_bf16 v[58:61], v[146:149], v[178:181], v[58:61]
	v_mfma_f32_16x16x32_bf16 v[50:53], v[154:157], v[178:181], v[50:53]
	v_mfma_f32_16x16x32_bf16 v[42:45], v[146:149], v[186:189], v[42:45]
	v_mfma_f32_16x16x32_bf16 v[34:37], v[154:157], v[186:189], v[34:37]
	v_mfma_f32_16x16x32_bf16 v[26:29], v[146:149], v[194:197], v[26:29]
	v_mfma_f32_16x16x32_bf16 v[18:21], v[154:157], v[194:197], v[18:21]
	v_mfma_f32_16x16x32_bf16 v[10:13], v[146:149], v[202:205], v[10:13]
	v_mfma_f32_16x16x32_bf16 v[2:5], v[154:157], v[202:205], v[2:5]
	v_mfma_f32_16x16x32_bf16 v[62:65], v[158:161], v[174:177], v[62:65]
	v_mfma_f32_16x16x32_bf16 v[54:57], v[166:169], v[174:177], v[54:57]
	v_mfma_f32_16x16x32_bf16 v[46:49], v[158:161], v[182:185], v[46:49]
	v_mfma_f32_16x16x32_bf16 v[38:41], v[166:169], v[182:185], v[38:41]
	v_mfma_f32_16x16x32_bf16 v[30:33], v[158:161], v[190:193], v[30:33]
	v_mfma_f32_16x16x32_bf16 v[22:25], v[166:169], v[190:193], v[22:25]
	v_mfma_f32_16x16x32_bf16 v[14:17], v[158:161], v[198:201], v[14:17]
	v_mfma_f32_16x16x32_bf16 v[6:9], v[166:169], v[198:201], v[6:9]
	v_mfma_f32_16x16x32_bf16 v[62:65], v[162:165], v[178:181], v[62:65]
	v_mfma_f32_16x16x32_bf16 v[54:57], v[170:173], v[178:181], v[54:57]
	v_mfma_f32_16x16x32_bf16 v[46:49], v[162:165], v[186:189], v[46:49]
	v_mfma_f32_16x16x32_bf16 v[38:41], v[170:173], v[186:189], v[38:41]
	v_mfma_f32_16x16x32_bf16 v[30:33], v[162:165], v[194:197], v[30:33]
	v_mfma_f32_16x16x32_bf16 v[22:25], v[170:173], v[194:197], v[22:25]
	v_mfma_f32_16x16x32_bf16 v[14:17], v[162:165], v[202:205], v[14:17]
	v_mfma_f32_16x16x32_bf16 v[6:9], v[170:173], v[202:205], v[6:9]
	s_barrier
	s_setprio 0
	s_add_i32 s47, s47, 2
	s_add_u32 s4, s4, 0x100
	s_addc_u32 s5, s5, 0
	s_add_u32 s42, s42, 0x100
	s_addc_u32 s46, s46, 0
	s_cmp_gt_u32 s47, 13
	s_cbranch_scc0 .LBB0_783
	s_and_b64 vcc, exec, s[12:13]
	s_cbranch_vccz .LBB0_786
	s_barrier

.Lsw_f20b:
	s_waitcnt lgkmcnt(0)
	s_setprio 1
	s_barrier
	v_mfma_f32_16x16x32_bf16 v[126:129], v[146:149], v[178:181], v[126:129]
	v_mfma_f32_16x16x32_bf16 v[122:125], v[154:157], v[178:181], v[122:125]
	v_mfma_f32_16x16x32_bf16 v[110:113], v[146:149], v[186:189], v[110:113]
	v_mfma_f32_16x16x32_bf16 v[106:109], v[154:157], v[186:189], v[106:109]
	v_mfma_f32_16x16x32_bf16 v[94:97], v[146:149], v[194:197], v[94:97]
	v_mfma_f32_16x16x32_bf16 v[90:93], v[154:157], v[194:197], v[90:93]
	v_mfma_f32_16x16x32_bf16 v[78:81], v[146:149], v[202:205], v[78:81]
	v_mfma_f32_16x16x32_bf16 v[74:77], v[154:157], v[202:205], v[74:77]
	v_mfma_f32_16x16x32_bf16 v[126:129], v[150:153], v[182:185], v[126:129]
	v_mfma_f32_16x16x32_bf16 v[122:125], v[158:161], v[182:185], v[122:125]
	v_mfma_f32_16x16x32_bf16 v[110:113], v[150:153], v[190:193], v[110:113]
	v_mfma_f32_16x16x32_bf16 v[106:109], v[158:161], v[190:193], v[106:109]
	v_mfma_f32_16x16x32_bf16 v[94:97], v[150:153], v[198:201], v[94:97]
	v_mfma_f32_16x16x32_bf16 v[90:93], v[158:161], v[198:201], v[90:93]
	v_mfma_f32_16x16x32_bf16 v[78:81], v[150:153], v[222:225], v[78:81]
	v_mfma_f32_16x16x32_bf16 v[74:77], v[158:161], v[222:225], v[74:77]
	v_mfma_f32_16x16x32_bf16 v[118:121], v[162:165], v[178:181], v[118:121]
	v_mfma_f32_16x16x32_bf16 v[114:117], v[170:173], v[178:181], v[114:117]
	v_mfma_f32_16x16x32_bf16 v[102:105], v[162:165], v[186:189], v[102:105]
	v_mfma_f32_16x16x32_bf16 v[98:101], v[170:173], v[186:189], v[98:101]
	v_mfma_f32_16x16x32_bf16 v[86:89], v[162:165], v[194:197], v[86:89]
	v_mfma_f32_16x16x32_bf16 v[82:85], v[170:173], v[194:197], v[82:85]
	v_mfma_f32_16x16x32_bf16 v[70:73], v[162:165], v[202:205], v[70:73]
	v_mfma_f32_16x16x32_bf16 v[66:69], v[170:173], v[202:205], v[66:69]
	v_mfma_f32_16x16x32_bf16 v[118:121], v[166:169], v[182:185], v[118:121]
	v_mfma_f32_16x16x32_bf16 v[114:117], v[174:177], v[182:185], v[114:117]
	v_mfma_f32_16x16x32_bf16 v[102:105], v[166:169], v[190:193], v[102:105]
	v_mfma_f32_16x16x32_bf16 v[98:101], v[174:177], v[190:193], v[98:101]
	v_mfma_f32_16x16x32_bf16 v[86:89], v[166:169], v[198:201], v[86:89]
	v_mfma_f32_16x16x32_bf16 v[82:85], v[174:177], v[198:201], v[82:85]
	v_mfma_f32_16x16x32_bf16 v[70:73], v[166:169], v[222:225], v[70:73]
	v_mfma_f32_16x16x32_bf16 v[66:69], v[174:177], v[222:225], v[66:69]
	s_barrier
	s_setprio 0
	s_add_i32 s18, s47, s24
	v_lshl_add_u64 v[142:143], s[20:21], 0, v[130:131]
	s_mov_b32 m0, s18
	ds_read_b128 v[178:181], v144 offset:16384
	ds_read_b128 v[182:185], v144 offset:17408
	ds_read_b128 v[186:189], v144 offset:18432
	ds_read_b128 v[190:193], v144 offset:19456
	ds_read_b128 v[194:197], v144 offset:20480
	ds_read_b128 v[198:201], v144 offset:21504
	ds_read_b128 v[202:205], v144 offset:22528
	ds_read_b128 v[222:225], v144 offset:23552
	global_load_lds_dwordx4 v[142:143], off
	s_add_i32 m0, s18, 0x2000
	s_add_u32 s18, s20, 0xb0000
	v_lshl_add_u64 v[206:207], s[20:21], 0, v[132:133]
	s_addc_u32 s19, s21, 0
	s_add_i32 s47, s48, s24
	global_load_lds_dwordx4 v[206:207], off
	v_lshl_add_u64 v[218:219], s[18:19], 0, v[130:131]
	s_mov_b32 m0, s47
	v_lshl_add_u64 v[226:227], s[22:23], 0, v[132:133]
	global_load_lds_dwordx4 v[218:219], off
	v_lshl_add_u64 v[218:219], s[18:19], 0, v[132:133]
	s_add_i32 m0, s47, 0x2000
	s_nop 0
	global_load_lds_dwordx4 v[218:219], off
	v_lshl_add_u64 v[218:219], s[22:23], 0, v[130:131]
	s_mov_b32 m0, s25
	s_nop 0
	global_load_lds_dwordx4 v[218:219], off
	s_mov_b32 m0, s26
	s_nop 0
	global_load_lds_dwordx4 v[226:227], off
	s_cmp_lg_u32 s46, -2
	s_cbranch_scc1 .Lsw_f21a
	s_cmp_eq_u32 s34, 1
	s_cbranch_scc1 .Lsw_f21a
	s_waitcnt vmcnt(24)
	s_branch .Lsw_f21b

.Lsw_f21b:
	s_waitcnt lgkmcnt(0)
	s_setprio 1
	s_barrier
	v_mfma_f32_16x16x32_bf16 v[62:65], v[146:149], v[178:181], v[62:65]
	v_mfma_f32_16x16x32_bf16 v[58:61], v[154:157], v[178:181], v[58:61]
	v_mfma_f32_16x16x32_bf16 v[46:49], v[146:149], v[186:189], v[46:49]
	v_mfma_f32_16x16x32_bf16 v[42:45], v[154:157], v[186:189], v[42:45]
	v_mfma_f32_16x16x32_bf16 v[30:33], v[146:149], v[194:197], v[30:33]
	v_mfma_f32_16x16x32_bf16 v[26:29], v[154:157], v[194:197], v[26:29]
	v_mfma_f32_16x16x32_bf16 v[14:17], v[146:149], v[202:205], v[14:17]
	v_mfma_f32_16x16x32_bf16 v[10:13], v[154:157], v[202:205], v[10:13]
	v_mfma_f32_16x16x32_bf16 v[62:65], v[150:153], v[182:185], v[62:65]
	v_mfma_f32_16x16x32_bf16 v[58:61], v[158:161], v[182:185], v[58:61]
	v_mfma_f32_16x16x32_bf16 v[46:49], v[150:153], v[190:193], v[46:49]
	v_mfma_f32_16x16x32_bf16 v[42:45], v[158:161], v[190:193], v[42:45]
	v_mfma_f32_16x16x32_bf16 v[30:33], v[150:153], v[198:201], v[30:33]
	v_mfma_f32_16x16x32_bf16 v[26:29], v[158:161], v[198:201], v[26:29]
	v_mfma_f32_16x16x32_bf16 v[14:17], v[150:153], v[222:225], v[14:17]
	v_mfma_f32_16x16x32_bf16 v[10:13], v[158:161], v[222:225], v[10:13]
	v_mfma_f32_16x16x32_bf16 v[54:57], v[162:165], v[178:181], v[54:57]
	v_mfma_f32_16x16x32_bf16 v[50:53], v[170:173], v[178:181], v[50:53]
	v_mfma_f32_16x16x32_bf16 v[38:41], v[162:165], v[186:189], v[38:41]
	v_mfma_f32_16x16x32_bf16 v[34:37], v[170:173], v[186:189], v[34:37]
	v_mfma_f32_16x16x32_bf16 v[22:25], v[162:165], v[194:197], v[22:25]
	v_mfma_f32_16x16x32_bf16 v[18:21], v[170:173], v[194:197], v[18:21]
	v_mfma_f32_16x16x32_bf16 v[6:9], v[162:165], v[202:205], v[6:9]
	v_mfma_f32_16x16x32_bf16 v[2:5], v[170:173], v[202:205], v[2:5]
	v_mfma_f32_16x16x32_bf16 v[54:57], v[166:169], v[182:185], v[54:57]
	v_mfma_f32_16x16x32_bf16 v[50:53], v[174:177], v[182:185], v[50:53]
	v_mfma_f32_16x16x32_bf16 v[38:41], v[166:169], v[190:193], v[38:41]
	v_mfma_f32_16x16x32_bf16 v[34:37], v[174:177], v[190:193], v[34:37]
	v_mfma_f32_16x16x32_bf16 v[22:25], v[166:169], v[198:201], v[22:25]
	v_mfma_f32_16x16x32_bf16 v[18:21], v[174:177], v[198:201], v[18:21]
	v_mfma_f32_16x16x32_bf16 v[6:9], v[166:169], v[222:225], v[6:9]
	v_mfma_f32_16x16x32_bf16 v[2:5], v[174:177], v[222:225], v[2:5]
	s_barrier
	s_setprio 0
	s_add_i32 s47, 0, 0x18000
	v_add_u32_e32 v0, s47, v135
	s_add_i32 s48, 0, 0x1c000
	ds_read_b128 v[146:149], v0
	ds_read_b128 v[150:153], v0 offset:1024
	ds_read_b128 v[154:157], v0 offset:2048
	ds_read_b128 v[158:161], v0 offset:3072
	v_add_u32_e32 v0, s48, v135
	ds_read_b128 v[162:165], v0
	ds_read_b128 v[166:169], v0 offset:1024
	ds_read_b128 v[170:173], v0 offset:2048
	ds_read_b128 v[174:177], v0 offset:3072
	s_add_u32 s18, s22, 0xb0000
	s_addc_u32 s19, s23, 0
	s_mov_b32 m0, s27
	v_lshl_add_u64 v[228:229], s[18:19], 0, v[130:131]
	ds_read_b128 v[178:181], v144 offset:32768
	ds_read_b128 v[182:185], v144 offset:33792
	ds_read_b128 v[186:189], v144 offset:34816
	ds_read_b128 v[190:193], v144 offset:35840
	ds_read_b128 v[194:197], v144 offset:36864
	ds_read_b128 v[198:201], v144 offset:37888
	ds_read_b128 v[202:205], v144 offset:38912
	ds_read_b128 v[222:225], v144 offset:39936
	global_load_lds_dwordx4 v[228:229], off
	v_lshl_add_u64 v[228:229], s[18:19], 0, v[132:133]
	s_mov_b32 m0, s28
	s_nop 0
	global_load_lds_dwordx4 v[228:229], off
	s_waitcnt vmcnt(8)
	s_waitcnt lgkmcnt(0)
	s_setprio 1
	s_barrier
	v_mfma_f32_16x16x32_bf16 v[126:129], v[146:149], v[178:181], v[126:129]
	v_mfma_f32_16x16x32_bf16 v[122:125], v[154:157], v[178:181], v[122:125]
	v_mfma_f32_16x16x32_bf16 v[110:113], v[146:149], v[186:189], v[110:113]
	v_mfma_f32_16x16x32_bf16 v[106:109], v[154:157], v[186:189], v[106:109]
	v_mfma_f32_16x16x32_bf16 v[94:97], v[146:149], v[194:197], v[94:97]
	v_mfma_f32_16x16x32_bf16 v[90:93], v[154:157], v[194:197], v[90:93]
	v_mfma_f32_16x16x32_bf16 v[78:81], v[146:149], v[202:205], v[78:81]
	v_mfma_f32_16x16x32_bf16 v[74:77], v[154:157], v[202:205], v[74:77]
	v_mfma_f32_16x16x32_bf16 v[126:129], v[150:153], v[182:185], v[126:129]
	v_mfma_f32_16x16x32_bf16 v[122:125], v[158:161], v[182:185], v[122:125]
	v_mfma_f32_16x16x32_bf16 v[110:113], v[150:153], v[190:193], v[110:113]
	v_mfma_f32_16x16x32_bf16 v[106:109], v[158:161], v[190:193], v[106:109]
	v_mfma_f32_16x16x32_bf16 v[94:97], v[150:153], v[198:201], v[94:97]
	v_mfma_f32_16x16x32_bf16 v[90:93], v[158:161], v[198:201], v[90:93]
	v_mfma_f32_16x16x32_bf16 v[78:81], v[150:153], v[222:225], v[78:81]
	v_mfma_f32_16x16x32_bf16 v[74:77], v[158:161], v[222:225], v[74:77]
	v_mfma_f32_16x16x32_bf16 v[118:121], v[162:165], v[178:181], v[118:121]
	v_mfma_f32_16x16x32_bf16 v[114:117], v[170:173], v[178:181], v[114:117]
	v_mfma_f32_16x16x32_bf16 v[102:105], v[162:165], v[186:189], v[102:105]
	v_mfma_f32_16x16x32_bf16 v[98:101], v[170:173], v[186:189], v[98:101]
	v_mfma_f32_16x16x32_bf16 v[86:89], v[162:165], v[194:197], v[86:89]
	v_mfma_f32_16x16x32_bf16 v[82:85], v[170:173], v[194:197], v[82:85]
	v_mfma_f32_16x16x32_bf16 v[70:73], v[162:165], v[202:205], v[70:73]
	v_mfma_f32_16x16x32_bf16 v[66:69], v[170:173], v[202:205], v[66:69]
	v_mfma_f32_16x16x32_bf16 v[118:121], v[166:169], v[182:185], v[118:121]
	v_mfma_f32_16x16x32_bf16 v[114:117], v[174:177], v[182:185], v[114:117]
	v_mfma_f32_16x16x32_bf16 v[102:105], v[166:169], v[190:193], v[102:105]
	v_mfma_f32_16x16x32_bf16 v[98:101], v[174:177], v[190:193], v[98:101]
	v_mfma_f32_16x16x32_bf16 v[86:89], v[166:169], v[198:201], v[86:89]
	v_mfma_f32_16x16x32_bf16 v[82:85], v[174:177], v[198:201], v[82:85]
	v_mfma_f32_16x16x32_bf16 v[70:73], v[166:169], v[222:225], v[70:73]
	v_mfma_f32_16x16x32_bf16 v[66:69], v[174:177], v[222:225], v[66:69]
	s_barrier
	s_setprio 0
	s_add_i32 s18, s47, s24
	v_lshl_add_u64 v[142:143], v[142:143], 0, s[44:45]
	s_mov_b32 m0, s18
	ds_read_b128 v[178:181], v144 offset:49152
	ds_read_b128 v[182:185], v144 offset:50176
	ds_read_b128 v[186:189], v144 offset:51200
	ds_read_b128 v[190:193], v144 offset:52224
	ds_read_b128 v[194:197], v144 offset:53248
	ds_read_b128 v[198:201], v144 offset:54272
	ds_read_b128 v[202:205], v144 offset:55296
	ds_read_b128 v[222:225], v144 offset:56320
	global_load_lds_dwordx4 v[142:143], off
	s_add_i32 m0, s18, 0x2000
	s_add_u32 s18, s20, 0xb0080
	v_lshl_add_u64 v[142:143], v[206:207], 0, s[44:45]
	s_addc_u32 s19, s21, 0
	s_add_i32 s20, s48, s24
	global_load_lds_dwordx4 v[142:143], off
	v_lshl_add_u64 v[142:143], s[18:19], 0, v[130:131]
	s_mov_b32 m0, s20
	s_nop 0
	global_load_lds_dwordx4 v[142:143], off
	v_lshl_add_u64 v[142:143], s[18:19], 0, v[132:133]
	s_add_i32 m0, s20, 0x2000
	s_nop 0
	global_load_lds_dwordx4 v[142:143], off
	v_lshl_add_u64 v[142:143], v[218:219], 0, s[44:45]
	s_mov_b32 m0, s31
	s_nop 0
	global_load_lds_dwordx4 v[142:143], off
	v_lshl_add_u64 v[142:143], v[226:227], 0, s[44:45]
	s_mov_b32 m0, s33
	s_nop 0
	global_load_lds_dwordx4 v[142:143], off
	s_waitcnt vmcnt(8)
	s_waitcnt lgkmcnt(0)
	s_setprio 1
	s_barrier
	v_mfma_f32_16x16x32_bf16 v[62:65], v[146:149], v[178:181], v[62:65]
	v_mfma_f32_16x16x32_bf16 v[58:61], v[154:157], v[178:181], v[58:61]
	v_mfma_f32_16x16x32_bf16 v[46:49], v[146:149], v[186:189], v[46:49]
	v_mfma_f32_16x16x32_bf16 v[42:45], v[154:157], v[186:189], v[42:45]
	v_mfma_f32_16x16x32_bf16 v[30:33], v[146:149], v[194:197], v[30:33]
	v_mfma_f32_16x16x32_bf16 v[26:29], v[154:157], v[194:197], v[26:29]
	v_mfma_f32_16x16x32_bf16 v[14:17], v[146:149], v[202:205], v[14:17]
	v_mfma_f32_16x16x32_bf16 v[10:13], v[154:157], v[202:205], v[10:13]
	v_mfma_f32_16x16x32_bf16 v[62:65], v[150:153], v[182:185], v[62:65]
	v_mfma_f32_16x16x32_bf16 v[58:61], v[158:161], v[182:185], v[58:61]
	v_mfma_f32_16x16x32_bf16 v[46:49], v[150:153], v[190:193], v[46:49]
	v_mfma_f32_16x16x32_bf16 v[42:45], v[158:161], v[190:193], v[42:45]
	v_mfma_f32_16x16x32_bf16 v[30:33], v[150:153], v[198:201], v[30:33]
	v_mfma_f32_16x16x32_bf16 v[26:29], v[158:161], v[198:201], v[26:29]
	v_mfma_f32_16x16x32_bf16 v[14:17], v[150:153], v[222:225], v[14:17]
	v_mfma_f32_16x16x32_bf16 v[10:13], v[158:161], v[222:225], v[10:13]
	v_mfma_f32_16x16x32_bf16 v[54:57], v[162:165], v[178:181], v[54:57]
	v_mfma_f32_16x16x32_bf16 v[50:53], v[170:173], v[178:181], v[50:53]
	v_mfma_f32_16x16x32_bf16 v[38:41], v[162:165], v[186:189], v[38:41]
	v_mfma_f32_16x16x32_bf16 v[34:37], v[170:173], v[186:189], v[34:37]
	v_mfma_f32_16x16x32_bf16 v[22:25], v[162:165], v[194:197], v[22:25]
	v_mfma_f32_16x16x32_bf16 v[18:21], v[170:173], v[194:197], v[18:21]
	v_mfma_f32_16x16x32_bf16 v[6:9], v[162:165], v[202:205], v[6:9]
	v_mfma_f32_16x16x32_bf16 v[2:5], v[170:173], v[202:205], v[2:5]
	v_mfma_f32_16x16x32_bf16 v[54:57], v[166:169], v[182:185], v[54:57]
	v_mfma_f32_16x16x32_bf16 v[50:53], v[174:177], v[182:185], v[50:53]
	v_mfma_f32_16x16x32_bf16 v[38:41], v[166:169], v[190:193], v[38:41]
	v_mfma_f32_16x16x32_bf16 v[34:37], v[174:177], v[190:193], v[34:37]
	v_mfma_f32_16x16x32_bf16 v[22:25], v[166:169], v[198:201], v[22:25]
	v_mfma_f32_16x16x32_bf16 v[18:21], v[174:177], v[198:201], v[18:21]
	v_mfma_f32_16x16x32_bf16 v[6:9], v[166:169], v[222:225], v[6:9]
	v_mfma_f32_16x16x32_bf16 v[2:5], v[174:177], v[222:225], v[2:5]
	s_barrier
	s_setprio 0
	s_add_i32 s46, s46, 2
	s_add_u32 s17, s17, 0x100
	s_addc_u32 s42, s42, 0
	s_cmp_gt_u32 s46, 41
	s_mov_b64 s[18:19], s[2:3]
	s_cbranch_scc0 .LBB0_849
	s_and_b64 vcc, exec, s[12:13]
	s_cbranch_vccz .LBB0_852
	s_barrier
